# mirror: static s_setprio 1 for waves 0-3 during the dil and GLA mixer phases (incl. mem_attn), reset after; placement preserved
# speedup vs baseline: 1.0070x; 1.0070x over previous
; __global__ void __launch_bounds__(NTHREADS, 2) megak(Params p) {
;     ...
;                 const int sl = st.b0 / SLAB_B, par = sl & 1;
;                 const bf16_t* PJ = PROJ + par * PROJ_SLAB;
;                 DilPrev pv{nullptr, nullptr, nullptr, nullptr, 0};
;                 if (sl > 0) pv = DilPrev{par ? OBUF : OBUF2, LSE + (par ^ 1) * LSE_SLAB, PROJ + (par ^ 1) * PROJ_SLAB, BR, st.b0 - SLAB_B};
;                 dil_attn_phase(lds, PJ, par ? OBUF2 : OBUF, LSE + par * LSE_SLAB, ROPE, SLAB_B * 288, pv, tid, wid, lane);
.LBB0_327:
	s_and_b64 vcc, exec, s[38:39]
	s_cbranch_vccnz .LBB0_437
	s_cmp_lg_u64 s[40:41], 0
	s_cselect_b64 s[50:51], -1, 0
	s_add_u32 s54, s30, s26
	s_addc_u32 s55, s31, s27
	s_mul_i32 s0, s78, 0x2ab
	s_mov_b32 s15, s78
	s_mov_b32 s68, 0x2aaaaaab
	s_movk_i32 s69, 0x81
	v_readlane_b32 s70, v254, 39
	s_mov_b32 s71, 0xffff
	s_mov_b32 s72, 0xff800000
	s_movk_i32 s73, 0x3000
	v_readfirstlane_b32 s100, v32
	s_nop 3
	s_cmpk_lt_u32 s100, 0x100
	s_cbranch_scc0 .Lprio_skip_dil
	s_setprio 1

; DI void gla_item(ldsp lds, const Params& p, const bf16_t* proj, bf16_t* obuf, const float* q0k0, int jl, int item, int tid, int wid, int lane) {
;     ...
;     float a00;
;     {
;         const float* qp = q0k0 + b * 768 + h * 96; const float* kp = qp + 384;
;         float t = qp[lane] * kp[lane] + (lane < 32 ? qp[64 + lane] * kp[64 + lane] : 0.f);
;         a00 = wave_sum(t) * 0.10206207261596575f;
;     }
;     f32x4 S[6];
; #pragma unroll
;     for (int i = 0; i < 6; ++i) S[i] = (f32x4){0.f, 0.f, 0.f, 0.f};
;     __syncthreads();
;     const int c0 = tid, c1 = tid + 512;
;     const int row0 = c0 / 12, ch0 = c0 - row0 * 12, row1 = c1 / 12, ch1 = c1 - row1 * 12;
;     const bool has1 = tid < 256;
;     u32x4 qreg0, kreg0, vreg0, qreg1 = (u32x4){0u, 0u, 0u, 0u}, kreg1 = qreg1, vreg1 = qreg1, greg = qreg1;
;     ...
;     GLA_LOAD_CHUNK(0);
.LBB0_482:
	s_or_b64 exec, exec, s[22:23]
	s_lshr_b32 s0, s19, 1
	s_waitcnt lgkmcnt(0)
	v_add_f32_e32 v13, v38, v39
	s_and_b32 s0, s0, 3
	v_mad_i64_i32 v[14:15], s[14:15], s74, v240, v[100:101]
	v_mov_b32_e32 v38, 0x180
	v_mul_f32_e32 v123, 0x3dd105ec, v13
	v_mad_u64_u32 v[124:125], s[14:15], s0, v38, v[14:15]
	v_mad_i64_i32 v[14:15], s[14:15], s74, v240, v[104:105]
	v_mov_b32_e32 v13, 0xc0
	v_mad_u64_u32 v[128:129], s[14:15], s0, v13, v[14:15]
	v_mad_i64_i32 v[14:15], s[14:15], s74, v240, v[106:107]
	v_mad_i64_i32 v[130:131], s[14:15], v36, s94, v[14:15]
	v_mad_i64_i32 v[14:15], s[14:15], s74, v240, v[110:111]
	v_mad_u64_u32 v[132:133], s[14:15], s0, v38, v[14:15]
	v_mad_i64_i32 v[14:15], s[14:15], s74, v240, v[114:115]
	v_mad_u64_u32 v[136:137], s[14:15], s0, v13, v[14:15]
	s_add_u32 s14, s26, s75
	s_addc_u32 s15, s27, 0
	s_mul_i32 s22, s0, 0x180
	s_lshl_b64 s[14:15], s[14:15], 1
	s_add_u32 s14, s14, s22
	s_mul_i32 s34, s74, 0x300000
	s_addc_u32 s15, s15, 0
	s_mul_hi_i32 s23, s74, 0x300000
	s_add_u32 s14, s14, s34
	s_addc_u32 s15, s15, s23
	v_mov_b32_e32 v13, 0x300000
	v_lshl_add_u64 v[138:139], s[14:15], 0, v[116:117]
	v_mad_i64_i32 v[14:15], s[14:15], s74, v13, v[118:119]
	v_mul_lo_u32 v37, v37, s71
	v_mad_u64_u32 v[140:141], s[14:15], s0, v38, v[14:15]
	v_mov_b32_e32 v14, v12
	v_mov_b32_e32 v15, v12
	s_mov_b32 s79, s1
	v_mov_b32_e32 v13, v12
	v_add_u32_e32 v198, v162, v37
	v_mov_b64_e32 v[38:39], v[14:15]
	v_mov_b64_e32 v[50:51], v[14:15]
	v_mov_b64_e32 v[54:55], v[14:15]
	v_mov_b64_e32 v[42:43], v[14:15]
	v_mov_b64_e32 v[46:47], v[14:15]
	v_mov_b64_e32 v[58:59], v[14:15]
	v_lshl_add_u64 v[126:127], v[102:103], 0, s[78:79]
	v_lshl_add_u64 v[134:135], v[112:113], 0, s[78:79]
	v_lshl_add_u64 v[142:143], v[120:121], 0, s[78:79]
	s_mov_b32 s0, 0
	v_mov_b64_e32 v[36:37], v[12:13]
	v_mov_b64_e32 v[48:49], v[12:13]
	v_mov_b64_e32 v[52:53], v[12:13]
	v_mov_b64_e32 v[40:41], v[12:13]
	v_mov_b64_e32 v[44:45], v[12:13]
	v_mov_b64_e32 v[56:57], v[12:13]
	v_readfirstlane_b32 s100, v32
	s_nop 3
	s_cmpk_lt_u32 s100, 0x100
	s_cbranch_scc0 .Lprio_skip_gla
	s_setprio 1
